# up GEMM epilogue stores marked nt (streaming U output)
# baseline (speedup 1.0000x reference)
; #define PG8_LAS __attribute__((address_space(3)))
;     __device__ __forceinline__ void operator()(const f32x4 (&acc)[2][2][4][2], const Unit& u, int ui, int wr, int wc, int fr, int fq) const {
;     ...
;         if (FOLD) { const PG8_LAS int* sl = (const PG8_LAS int*)(tb + 16384); pslot = sl[ui] * 256; const int cslot = sl[16 + ui] * 256 + wc * 32 + 8 * fq;
;             const PG8_LAS float* csl = (const PG8_LAS float*)(tb + 8192); const PG8_LAS float* bwl = (const PG8_LAS float*)(tb + 12288);
; #pragma unroll
;             for (int bj = 0; bj < 2; ++bj)
; #pragma unroll
;                 for (int n = 0; n < 2; ++n) { cv[bj][n] = *(const PG8_LAS f32x4*)(csl + cslot + bj * HALF + 4 * n); bv[bj][n] = *(const PG8_LAS f32x4*)(bwl + cslot + bj * HALF + 4 * n); } }
;     ...
;             for (int m = 0; m < 4; ++m) { const int row = row0 + ai * HALF + m * 16; const size_t off = (size_t)row * ldc + col0;
;                 float mu = 0.f, rs = 1.f; if (FOLD) { const f32x2_t ms = ((const PG8_LAS f32x2_t*)tb)[pslot + ai * HALF + wr * 64 + m * 16 + fr]; mu = ms.x; rs = ms.y; }
;                 float ssum = 0.f, ssq = 0.f;
; #pragma unroll
;                 for (int bj = 0; bj < 2; ++bj) { f32x4 v0 = acc[ai][bj][m][0], v1 = acc[ai][bj][m][1];
;                     if (FOLD && MODE != 2) { v0 = (v0 - mu * cv[bj][0]) * rs + bv[bj][0]; v1 = (v1 - mu * cv[bj][1]) * rs + bv[bj][1]; }
;                     if (MODE == 0) { v0 = v0 * sc; v1 = v1 * sc; }
;                     if (MODE == 1) { v0 = __builtin_elementwise_max(v0, (f32x4){0.f, 0.f, 0.f, 0.f}); v1 = __builtin_elementwise_max(v1, (f32x4){0.f, 0.f, 0.f, 0.f}); v0 = v0 * v0; v1 = v1 * v1; }
;                     if (MODE == 2) { const bf16x8 r = rr[m][bj];
;                         f32x4 h0 = (f32x4){(float)r[0], (float)r[1], (float)r[2], (float)r[3]}, h1 = (f32x4){(float)r[4], (float)r[5], (float)r[6], (float)r[7]};
;                         if (FOLD) { h0 = (h0 - mu) * rs * cv[bj][0] + bv[bj][0]; h1 = (h1 - mu) * rs * cv[bj][1] + bv[bj][1]; }
;                         v0 = v0 + alpha * h0; v1 = v1 + alpha * h1;
;                         ssum += (v0[0] + v0[1]) + (v0[2] + v0[3]) + (v1[0] + v1[1]) + (v1[2] + v1[3]);
;                         ssq += (v0[0] * v0[0] + v0[1] * v0[1]) + (v0[2] * v0[2] + v0[3] * v0[3]) + (v1[0] * v1[0] + v1[1] * v1[1]) + (v1[2] * v1[2] + v1[3] * v1[3]); }
.LBB0_989:
	s_lshl_b32 s12, s72, 2
	s_add_i32 s12, s12, 0
	s_add_i32 s12, s12, 0x24000
	v_mov_b32_e32 v134, s12
	ds_read2_b32 v[176:177], v134 offset1:16
	v_lshlrev_b32_e32 v134, 2, v182
	v_lshl_add_u32 v178, s71, 8, v1
	v_lshl_or_b32 v180, s58, 8, v182
	v_ashrrev_i32_e32 v181, 31, v180
	s_waitcnt lgkmcnt(0)
	v_lshl_or_b32 v134, v177, 10, v134
	v_add_u32_e32 v134, 0, v134
	v_add_u32_e32 v135, 0x22000, v134
	v_add_u32_e32 v138, 0x23000, v134
	v_lshl_add_u32 v185, v176, 11, v183
	ds_read_b128 v[158:161], v138
	ds_read_b128 v[150:153], v138 offset:16
	ds_read_b128 v[162:165], v135
	ds_read_b128 v[154:157], v135 offset:16
	ds_read_b128 v[142:145], v135 offset:512
	ds_read_b128 v[134:137], v135 offset:528
	ds_read_b128 v[146:149], v138 offset:512
	ds_read_b128 v[138:141], v138 offset:528
	ds_read2_b64 v[186:189], v185 offset1:16
	s_waitcnt lgkmcnt(0)
	v_xor_b32_e32 v165, 0x80000000, v165
	v_xor_b32_e32 v164, 0x80000000, v164
	v_ashrrev_i32_e32 v179, 31, v178
	v_lshl_add_u64 v[180:181], v[180:181], 1, s[96:97]
	v_pk_fma_f32 v[130:131], v[162:163], v[186:187], v[130:131] op_sel_hi:[1,0,1] neg_lo:[1,0,0] neg_hi:[1,0,0]
	v_pk_fma_f32 v[132:133], v[164:165], v[186:187], v[132:133] op_sel_hi:[1,0,1]
	v_pk_fma_f32 v[190:191], v[186:187], v[130:131], v[158:159] op_sel:[1,0,0]
	v_xor_b32_e32 v131, 0x80000000, v157
	v_xor_b32_e32 v130, 0x80000000, v156
	v_pk_fma_f32 v[128:129], v[130:131], v[186:187], v[128:129] op_sel_hi:[1,0,1]
	v_pk_fma_f32 v[126:127], v[154:155], v[186:187], v[126:127] op_sel_hi:[1,0,1] neg_lo:[1,0,0] neg_hi:[1,0,0]
	v_pk_fma_f32 v[132:133], v[186:187], v[132:133], v[160:161] op_sel:[1,0,0]
	v_pk_fma_f32 v[128:129], v[186:187], v[128:129], v[152:153] op_sel:[1,0,0]
	v_pk_fma_f32 v[126:127], v[186:187], v[126:127], v[150:151] op_sel:[1,0,0]
	v_max_f32_e32 v133, 0, v133
	v_max_f32_e32 v132, 0, v132
	v_max_f32_e32 v157, 0, v191
	v_max_f32_e32 v156, 0, v190
	v_max_f32_e32 v129, 0, v129
	v_max_f32_e32 v128, 0, v128
	v_max_f32_e32 v127, 0, v127
	v_max_f32_e32 v126, 0, v126
	v_lshlrev_b64 v[176:177], 13, v[178:179]
	v_pk_mul_f32 v[132:133], v[132:133], v[132:133]
	v_pk_mul_f32 v[156:157], v[156:157], v[156:157]
	v_pk_mul_f32 v[190:191], v[128:129], v[128:129]
	v_pk_mul_f32 v[128:129], v[126:127], v[126:127]
	v_lshl_add_u64 v[176:177], v[180:181], 0, v[176:177]
	v_cvt_pk_f16_f32 v126, v156, v157
	v_cvt_pk_f16_f32 v127, v132, v133
	v_cvt_pk_f16_f32 v128, v128, v129
	v_cvt_pk_f16_f32 v129, v190, v191
	v_pk_fma_f32 v[122:123], v[142:143], v[186:187], v[122:123] op_sel_hi:[1,0,1] neg_lo:[1,0,0] neg_hi:[1,0,0]
	global_store_dwordx4 v[176:177], v[126:129], off nt
	v_pk_fma_f32 v[118:119], v[134:135], v[186:187], v[118:119] op_sel_hi:[1,0,1] neg_lo:[1,0,0] neg_hi:[1,0,0]
	v_pk_fma_f32 v[116:117], v[164:165], v[188:189], v[116:117] op_sel_hi:[1,0,1]
	v_xor_b32_e32 v127, 0x80000000, v145
	v_xor_b32_e32 v126, 0x80000000, v144
	v_pk_fma_f32 v[128:129], v[186:187], v[122:123], v[146:147] op_sel:[1,0,0]
	v_xor_b32_e32 v123, 0x80000000, v137
	v_xor_b32_e32 v122, 0x80000000, v136
	v_pk_fma_f32 v[124:125], v[126:127], v[186:187], v[124:125] op_sel_hi:[1,0,1]
	v_pk_fma_f32 v[120:121], v[122:123], v[186:187], v[120:121] op_sel_hi:[1,0,1]
	v_pk_fma_f32 v[124:125], v[186:187], v[124:125], v[148:149] op_sel:[1,0,0]
	v_pk_fma_f32 v[120:121], v[186:187], v[120:121], v[140:141] op_sel:[1,0,0]
	v_pk_fma_f32 v[118:119], v[186:187], v[118:119], v[138:139] op_sel:[1,0,0]
	v_max_f32_e32 v125, 0, v125
	v_max_f32_e32 v124, 0, v124
	v_max_f32_e32 v129, 0, v129
	v_max_f32_e32 v128, 0, v128
	v_max_f32_e32 v121, 0, v121
	v_max_f32_e32 v120, 0, v120
	v_max_f32_e32 v119, 0, v119
	v_max_f32_e32 v118, 0, v118
	v_pk_mul_f32 v[124:125], v[124:125], v[124:125]
	v_pk_mul_f32 v[128:129], v[128:129], v[128:129]
	v_pk_mul_f32 v[132:133], v[120:121], v[120:121]
	v_pk_mul_f32 v[120:121], v[118:119], v[118:119]
	v_cvt_pk_f16_f32 v118, v128, v129
	v_cvt_pk_f16_f32 v119, v124, v125
	v_cvt_pk_f16_f32 v120, v120, v121
	v_cvt_pk_f16_f32 v121, v132, v133
	v_pk_fma_f32 v[114:115], v[162:163], v[188:189], v[114:115] op_sel_hi:[1,0,1] neg_lo:[1,0,0] neg_hi:[1,0,0]
	v_pk_fma_f32 v[112:113], v[130:131], v[188:189], v[112:113] op_sel_hi:[1,0,1]
	v_pk_fma_f32 v[110:111], v[154:155], v[188:189], v[110:111] op_sel_hi:[1,0,1] neg_lo:[1,0,0] neg_hi:[1,0,0]
	global_store_dwordx4 v[176:177], v[118:121], off offset:256 nt
	v_pk_fma_f32 v[116:117], v[188:189], v[116:117], v[160:161] op_sel:[1,0,0]
	v_pk_fma_f32 v[114:115], v[188:189], v[114:115], v[158:159] op_sel:[1,0,0]
	v_or_b32_e32 v118, 16, v178
	v_pk_fma_f32 v[112:113], v[188:189], v[112:113], v[152:153] op_sel:[1,0,0]
	v_pk_fma_f32 v[110:111], v[188:189], v[110:111], v[150:151] op_sel:[1,0,0]
	v_ashrrev_i32_e32 v119, 31, v118
	v_max_f32_e32 v117, 0, v117
	v_max_f32_e32 v116, 0, v116
	v_max_f32_e32 v115, 0, v115
	v_max_f32_e32 v114, 0, v114
	v_max_f32_e32 v113, 0, v113
	v_max_f32_e32 v112, 0, v112
	v_max_f32_e32 v111, 0, v111
	v_max_f32_e32 v110, 0, v110
	v_pk_fma_f32 v[108:109], v[126:127], v[188:189], v[108:109] op_sel_hi:[1,0,1]
	v_pk_fma_f32 v[106:107], v[142:143], v[188:189], v[106:107] op_sel_hi:[1,0,1] neg_lo:[1,0,0] neg_hi:[1,0,0]
	v_pk_fma_f32 v[104:105], v[122:123], v[188:189], v[104:105] op_sel_hi:[1,0,1]
	v_pk_fma_f32 v[102:103], v[134:135], v[188:189], v[102:103] op_sel_hi:[1,0,1] neg_lo:[1,0,0] neg_hi:[1,0,0]
	v_lshlrev_b64 v[118:119], 13, v[118:119]
	v_pk_mul_f32 v[116:117], v[116:117], v[116:117]
	v_pk_mul_f32 v[114:115], v[114:115], v[114:115]
	v_pk_mul_f32 v[120:121], v[112:113], v[112:113]
	v_pk_mul_f32 v[112:113], v[110:111], v[110:111]
	v_pk_fma_f32 v[108:109], v[188:189], v[108:109], v[148:149] op_sel:[1,0,0]
	v_pk_fma_f32 v[106:107], v[188:189], v[106:107], v[146:147] op_sel:[1,0,0]
	v_pk_fma_f32 v[104:105], v[188:189], v[104:105], v[140:141] op_sel:[1,0,0]
	v_pk_fma_f32 v[102:103], v[188:189], v[102:103], v[138:139] op_sel:[1,0,0]
	v_lshl_add_u64 v[118:119], v[180:181], 0, v[118:119]
	v_cvt_pk_f16_f32 v110, v114, v115
	v_cvt_pk_f16_f32 v111, v116, v117
	v_cvt_pk_f16_f32 v112, v112, v113
	v_cvt_pk_f16_f32 v113, v120, v121
	v_max_f32_e32 v109, 0, v109
	v_max_f32_e32 v108, 0, v108
	v_max_f32_e32 v107, 0, v107
	v_max_f32_e32 v106, 0, v106
	v_max_f32_e32 v105, 0, v105
	v_max_f32_e32 v104, 0, v104
	v_max_f32_e32 v103, 0, v103
	v_max_f32_e32 v102, 0, v102
	global_store_dwordx4 v[118:119], v[110:113], off nt
	v_pk_mul_f32 v[108:109], v[108:109], v[108:109]
	v_pk_mul_f32 v[106:107], v[106:107], v[106:107]
	v_pk_mul_f32 v[110:111], v[104:105], v[104:105]
	v_pk_mul_f32 v[104:105], v[102:103], v[102:103]
	v_cvt_pk_f16_f32 v102, v106, v107
	v_cvt_pk_f16_f32 v103, v108, v109
	v_cvt_pk_f16_f32 v104, v104, v105
	v_cvt_pk_f16_f32 v105, v110, v111
	global_store_dwordx4 v[118:119], v[102:105], off offset:256 nt
	ds_read2_b64 v[102:105], v185 offset0:32 offset1:48
	v_or_b32_e32 v106, 32, v178
	v_ashrrev_i32_e32 v107, 31, v106
	v_lshlrev_b64 v[106:107], 13, v[106:107]
	v_lshl_add_u64 v[106:107], v[180:181], 0, v[106:107]
	s_waitcnt lgkmcnt(0)
; #define PG8_LAS __attribute__((address_space(3)))
;     __device__ __forceinline__ void operator()(const f32x4 (&acc)[2][2][4][2], const Unit& u, int ui, int wr, int wc, int fr, int fq) const {
;     ...
;             for (int m = 0; m < 4; ++m) { const int row = row0 + ai * HALF + m * 16; const size_t off = (size_t)row * ldc + col0;
;                 float mu = 0.f, rs = 1.f; if (FOLD) { const f32x2_t ms = ((const PG8_LAS f32x2_t*)tb)[pslot + ai * HALF + wr * 64 + m * 16 + fr]; mu = ms.x; rs = ms.y; }
;                 float ssum = 0.f, ssq = 0.f;
; #pragma unroll
;                 for (int bj = 0; bj < 2; ++bj) { f32x4 v0 = acc[ai][bj][m][0], v1 = acc[ai][bj][m][1];
;                     if (FOLD && MODE != 2) { v0 = (v0 - mu * cv[bj][0]) * rs + bv[bj][0]; v1 = (v1 - mu * cv[bj][1]) * rs + bv[bj][1]; }
;                     if (MODE == 0) { v0 = v0 * sc; v1 = v1 * sc; }
;                     if (MODE == 1) { v0 = __builtin_elementwise_max(v0, (f32x4){0.f, 0.f, 0.f, 0.f}); v1 = __builtin_elementwise_max(v1, (f32x4){0.f, 0.f, 0.f, 0.f}); v0 = v0 * v0; v1 = v1 * v1; }
;                     if (MODE == 2) { const bf16x8 r = rr[m][bj];
;                         f32x4 h0 = (f32x4){(float)r[0], (float)r[1], (float)r[2], (float)r[3]}, h1 = (f32x4){(float)r[4], (float)r[5], (float)r[6], (float)r[7]};
;                         if (FOLD) { h0 = (h0 - mu) * rs * cv[bj][0] + bv[bj][0]; h1 = (h1 - mu) * rs * cv[bj][1] + bv[bj][1]; }
;                         v0 = v0 + alpha * h0; v1 = v1 + alpha * h1;
;                         ssum += (v0[0] + v0[1]) + (v0[2] + v0[3]) + (v1[0] + v1[1]) + (v1[2] + v1[3]);
;                         ssq += (v0[0] * v0[0] + v0[1] * v0[1]) + (v0[2] * v0[2] + v0[3] * v0[3]) + (v1[0] * v1[0] + v1[1] * v1[1]) + (v1[2] * v1[2] + v1[3] * v1[3]); }
;                     u32x4 w; w.x = pk2h(v0[0], v0[1]); w.y = pk2h(v0[2], v0[3]); w.z = pk2h(v1[0], v1[1]); w.w = pk2h(v1[2], v1[3]);
;                     if (MODE == 0 && hm) { const int cc = col0 + bj * HALF; *(u32x4*)(base + ((size_t)(row >> 11) * 16 + (cc >> 6)) * 131072 + (size_t)(row & 2047) * 64 + (cc & 63)) = w; }
;                     else *(u32x4*)(base + off + bj * HALF) = w; }
	v_pk_fma_f32 v[100:101], v[164:165], v[102:103], v[100:101] op_sel_hi:[1,0,1]
	v_pk_fma_f32 v[98:99], v[162:163], v[102:103], v[98:99] op_sel_hi:[1,0,1] neg_lo:[1,0,0] neg_hi:[1,0,0]
	v_pk_fma_f32 v[96:97], v[130:131], v[102:103], v[96:97] op_sel_hi:[1,0,1]
	v_pk_fma_f32 v[94:95], v[154:155], v[102:103], v[94:95] op_sel_hi:[1,0,1] neg_lo:[1,0,0] neg_hi:[1,0,0]
	v_pk_fma_f32 v[100:101], v[102:103], v[100:101], v[160:161] op_sel:[1,0,0]
	v_pk_fma_f32 v[98:99], v[102:103], v[98:99], v[158:159] op_sel:[1,0,0]
	v_pk_fma_f32 v[96:97], v[102:103], v[96:97], v[152:153] op_sel:[1,0,0]
	v_pk_fma_f32 v[94:95], v[102:103], v[94:95], v[150:151] op_sel:[1,0,0]
	v_max_f32_e32 v101, 0, v101
	v_max_f32_e32 v100, 0, v100
	v_max_f32_e32 v99, 0, v99
	v_max_f32_e32 v98, 0, v98
	v_max_f32_e32 v97, 0, v97
	v_max_f32_e32 v96, 0, v96
	v_max_f32_e32 v95, 0, v95
	v_max_f32_e32 v94, 0, v94
	v_pk_fma_f32 v[92:93], v[126:127], v[102:103], v[92:93] op_sel_hi:[1,0,1]
	v_pk_fma_f32 v[90:91], v[142:143], v[102:103], v[90:91] op_sel_hi:[1,0,1] neg_lo:[1,0,0] neg_hi:[1,0,0]
	v_pk_fma_f32 v[88:89], v[122:123], v[102:103], v[88:89] op_sel_hi:[1,0,1]
	v_pk_fma_f32 v[86:87], v[134:135], v[102:103], v[86:87] op_sel_hi:[1,0,1] neg_lo:[1,0,0] neg_hi:[1,0,0]
	v_pk_mul_f32 v[100:101], v[100:101], v[100:101]
	v_pk_mul_f32 v[98:99], v[98:99], v[98:99]
	v_pk_mul_f32 v[108:109], v[96:97], v[96:97]
	v_pk_mul_f32 v[96:97], v[94:95], v[94:95]
	v_pk_fma_f32 v[92:93], v[102:103], v[92:93], v[148:149] op_sel:[1,0,0]
	v_pk_fma_f32 v[90:91], v[102:103], v[90:91], v[146:147] op_sel:[1,0,0]
	v_pk_fma_f32 v[88:89], v[102:103], v[88:89], v[140:141] op_sel:[1,0,0]
	v_pk_fma_f32 v[86:87], v[102:103], v[86:87], v[138:139] op_sel:[1,0,0]
	v_cvt_pk_f16_f32 v94, v98, v99
	v_cvt_pk_f16_f32 v95, v100, v101
	v_cvt_pk_f16_f32 v96, v96, v97
	v_cvt_pk_f16_f32 v97, v108, v109
	v_max_f32_e32 v93, 0, v93
	v_max_f32_e32 v92, 0, v92
	v_max_f32_e32 v91, 0, v91
	v_max_f32_e32 v90, 0, v90
	v_max_f32_e32 v89, 0, v89
	v_max_f32_e32 v88, 0, v88
	v_max_f32_e32 v87, 0, v87
	v_max_f32_e32 v86, 0, v86
	global_store_dwordx4 v[106:107], v[94:97], off nt
	v_pk_mul_f32 v[92:93], v[92:93], v[92:93]
	v_pk_mul_f32 v[90:91], v[90:91], v[90:91]
	v_pk_mul_f32 v[94:95], v[88:89], v[88:89]
	v_pk_mul_f32 v[88:89], v[86:87], v[86:87]
	v_cvt_pk_f16_f32 v86, v90, v91
	v_cvt_pk_f16_f32 v87, v92, v93
	v_cvt_pk_f16_f32 v88, v88, v89
	v_cvt_pk_f16_f32 v89, v94, v95
	v_pk_fma_f32 v[84:85], v[164:165], v[104:105], v[84:85] op_sel_hi:[1,0,1]
	v_pk_fma_f32 v[82:83], v[162:163], v[104:105], v[82:83] op_sel_hi:[1,0,1] neg_lo:[1,0,0] neg_hi:[1,0,0]
	v_pk_fma_f32 v[80:81], v[130:131], v[104:105], v[80:81] op_sel_hi:[1,0,1]
	v_pk_fma_f32 v[78:79], v[154:155], v[104:105], v[78:79] op_sel_hi:[1,0,1] neg_lo:[1,0,0] neg_hi:[1,0,0]
	global_store_dwordx4 v[106:107], v[86:89], off offset:256 nt
	v_pk_fma_f32 v[84:85], v[104:105], v[84:85], v[160:161] op_sel:[1,0,0]
	v_pk_fma_f32 v[82:83], v[104:105], v[82:83], v[158:159] op_sel:[1,0,0]
	v_or_b32_e32 v86, 48, v178
	v_pk_fma_f32 v[80:81], v[104:105], v[80:81], v[152:153] op_sel:[1,0,0]
	v_pk_fma_f32 v[78:79], v[104:105], v[78:79], v[150:151] op_sel:[1,0,0]
	v_pk_fma_f32 v[76:77], v[126:127], v[104:105], v[76:77] op_sel_hi:[1,0,1]
	v_pk_fma_f32 v[74:75], v[142:143], v[104:105], v[74:75] op_sel_hi:[1,0,1] neg_lo:[1,0,0] neg_hi:[1,0,0]
	v_ashrrev_i32_e32 v87, 31, v86
	v_max_f32_e32 v85, 0, v85
	v_max_f32_e32 v84, 0, v84
	v_max_f32_e32 v83, 0, v83
	v_max_f32_e32 v82, 0, v82
	v_max_f32_e32 v81, 0, v81
	v_max_f32_e32 v80, 0, v80
	v_max_f32_e32 v79, 0, v79
	v_max_f32_e32 v78, 0, v78
	v_pk_fma_f32 v[76:77], v[104:105], v[76:77], v[148:149] op_sel:[1,0,0]
	v_pk_fma_f32 v[74:75], v[104:105], v[74:75], v[146:147] op_sel:[1,0,0]
	v_pk_fma_f32 v[72:73], v[122:123], v[104:105], v[72:73] op_sel_hi:[1,0,1]
	v_pk_fma_f32 v[70:71], v[134:135], v[104:105], v[70:71] op_sel_hi:[1,0,1] neg_lo:[1,0,0] neg_hi:[1,0,0]
	v_lshlrev_b64 v[86:87], 13, v[86:87]
	v_pk_mul_f32 v[84:85], v[84:85], v[84:85]
	v_pk_mul_f32 v[82:83], v[82:83], v[82:83]
	v_pk_mul_f32 v[88:89], v[80:81], v[80:81]
	v_pk_mul_f32 v[80:81], v[78:79], v[78:79]
	v_pk_fma_f32 v[72:73], v[104:105], v[72:73], v[140:141] op_sel:[1,0,0]
	v_pk_fma_f32 v[70:71], v[104:105], v[70:71], v[138:139] op_sel:[1,0,0]
	v_max_f32_e32 v77, 0, v77
	v_max_f32_e32 v76, 0, v76
	v_max_f32_e32 v75, 0, v75
	v_max_f32_e32 v74, 0, v74
	v_lshl_add_u64 v[86:87], v[180:181], 0, v[86:87]
	v_cvt_pk_f16_f32 v78, v82, v83
	v_cvt_pk_f16_f32 v79, v84, v85
	v_cvt_pk_f16_f32 v80, v80, v81
	v_cvt_pk_f16_f32 v81, v88, v89
	v_max_f32_e32 v73, 0, v73
	v_max_f32_e32 v72, 0, v72
	v_max_f32_e32 v71, 0, v71
	v_max_f32_e32 v70, 0, v70
	v_pk_mul_f32 v[76:77], v[76:77], v[76:77]
	v_pk_mul_f32 v[74:75], v[74:75], v[74:75]
	global_store_dwordx4 v[86:87], v[78:81], off nt
	s_mov_b64 s[12:13], 0x100000
	v_readlane_b32 s54, v255, 25
	v_pk_mul_f32 v[78:79], v[72:73], v[72:73]
	v_pk_mul_f32 v[72:73], v[70:71], v[70:71]
	v_cvt_pk_f16_f32 v70, v74, v75
	v_cvt_pk_f16_f32 v71, v76, v77
	ds_read2_b64 v[74:77], v185 offset0:128 offset1:144
	v_cvt_pk_f16_f32 v72, v72, v73
	v_cvt_pk_f16_f32 v73, v78, v79
	global_store_dwordx4 v[86:87], v[70:73], off offset:256 nt
	s_mov_b64 s[22:23], -1
	s_waitcnt lgkmcnt(0)
; #define PG8_LAS __attribute__((address_space(3)))
;     __device__ __forceinline__ void operator()(const f32x4 (&acc)[2][2][4][2], const Unit& u, int ui, int wr, int wc, int fr, int fq) const {
;     ...
;             for (int m = 0; m < 4; ++m) { const int row = row0 + ai * HALF + m * 16; const size_t off = (size_t)row * ldc + col0;
;                 float mu = 0.f, rs = 1.f; if (FOLD) { const f32x2_t ms = ((const PG8_LAS f32x2_t*)tb)[pslot + ai * HALF + wr * 64 + m * 16 + fr]; mu = ms.x; rs = ms.y; }
;                 float ssum = 0.f, ssq = 0.f;
; #pragma unroll
;                 for (int bj = 0; bj < 2; ++bj) { f32x4 v0 = acc[ai][bj][m][0], v1 = acc[ai][bj][m][1];
;                     if (FOLD && MODE != 2) { v0 = (v0 - mu * cv[bj][0]) * rs + bv[bj][0]; v1 = (v1 - mu * cv[bj][1]) * rs + bv[bj][1]; }
;                     if (MODE == 0) { v0 = v0 * sc; v1 = v1 * sc; }
;                     if (MODE == 1) { v0 = __builtin_elementwise_max(v0, (f32x4){0.f, 0.f, 0.f, 0.f}); v1 = __builtin_elementwise_max(v1, (f32x4){0.f, 0.f, 0.f, 0.f}); v0 = v0 * v0; v1 = v1 * v1; }
;                     if (MODE == 2) { const bf16x8 r = rr[m][bj];
;                         f32x4 h0 = (f32x4){(float)r[0], (float)r[1], (float)r[2], (float)r[3]}, h1 = (f32x4){(float)r[4], (float)r[5], (float)r[6], (float)r[7]};
;                         if (FOLD) { h0 = (h0 - mu) * rs * cv[bj][0] + bv[bj][0]; h1 = (h1 - mu) * rs * cv[bj][1] + bv[bj][1]; }
;                         v0 = v0 + alpha * h0; v1 = v1 + alpha * h1;
;                         ssum += (v0[0] + v0[1]) + (v0[2] + v0[3]) + (v1[0] + v1[1]) + (v1[2] + v1[3]);
;                         ssq += (v0[0] * v0[0] + v0[1] * v0[1]) + (v0[2] * v0[2] + v0[3] * v0[3]) + (v1[0] * v1[0] + v1[1] * v1[1]) + (v1[2] * v1[2] + v1[3] * v1[3]); }
;                     u32x4 w; w.x = pk2h(v0[0], v0[1]); w.y = pk2h(v0[2], v0[3]); w.z = pk2h(v1[0], v1[1]); w.w = pk2h(v1[2], v1[3]);
;                     if (MODE == 0 && hm) { const int cc = col0 + bj * HALF; *(u32x4*)(base + ((size_t)(row >> 11) * 16 + (cc >> 6)) * 131072 + (size_t)(row & 2047) * 64 + (cc & 63)) = w; }
;                     else *(u32x4*)(base + off + bj * HALF) = w; }
	v_pk_fma_f32 v[66:67], v[162:163], v[74:75], v[66:67] op_sel_hi:[1,0,1] neg_lo:[1,0,0] neg_hi:[1,0,0]
	v_pk_fma_f32 v[68:69], v[164:165], v[74:75], v[68:69] op_sel_hi:[1,0,1]
	v_pk_fma_f32 v[66:67], v[74:75], v[66:67], v[158:159] op_sel:[1,0,0]
	v_pk_fma_f32 v[64:65], v[130:131], v[74:75], v[64:65] op_sel_hi:[1,0,1]
	v_pk_fma_f32 v[62:63], v[154:155], v[74:75], v[62:63] op_sel_hi:[1,0,1] neg_lo:[1,0,0] neg_hi:[1,0,0]
	v_pk_fma_f32 v[68:69], v[74:75], v[68:69], v[160:161] op_sel:[1,0,0]
	v_pk_fma_f32 v[64:65], v[74:75], v[64:65], v[152:153] op_sel:[1,0,0]
	v_pk_fma_f32 v[62:63], v[74:75], v[62:63], v[150:151] op_sel:[1,0,0]
	v_max_f32_e32 v67, 0, v67
	v_max_f32_e32 v66, 0, v66
	v_lshl_add_u64 v[70:71], v[176:177], 0, s[12:13]
	v_max_f32_e32 v69, 0, v69
	v_max_f32_e32 v68, 0, v68
	v_max_f32_e32 v65, 0, v65
	v_max_f32_e32 v64, 0, v64
	v_max_f32_e32 v63, 0, v63
	v_max_f32_e32 v62, 0, v62
	v_pk_mul_f32 v[66:67], v[66:67], v[66:67]
	s_mov_b32 s12, 0x100000
	v_pk_fma_f32 v[60:61], v[126:127], v[74:75], v[60:61] op_sel_hi:[1,0,1]
	v_pk_fma_f32 v[58:59], v[142:143], v[74:75], v[58:59] op_sel_hi:[1,0,1] neg_lo:[1,0,0] neg_hi:[1,0,0]
	v_pk_fma_f32 v[56:57], v[122:123], v[74:75], v[56:57] op_sel_hi:[1,0,1]
	v_pk_fma_f32 v[54:55], v[134:135], v[74:75], v[54:55] op_sel_hi:[1,0,1] neg_lo:[1,0,0] neg_hi:[1,0,0]
	v_pk_mul_f32 v[68:69], v[68:69], v[68:69]
	v_pk_mul_f32 v[72:73], v[64:65], v[64:65]
	v_pk_mul_f32 v[64:65], v[62:63], v[62:63]
	v_cvt_pk_f16_f32 v62, v66, v67
	v_add_co_u32_e32 v66, vcc, s12, v176
	v_pk_fma_f32 v[60:61], v[74:75], v[60:61], v[148:149] op_sel:[1,0,0]
	v_pk_fma_f32 v[58:59], v[74:75], v[58:59], v[146:147] op_sel:[1,0,0]
	v_pk_fma_f32 v[56:57], v[74:75], v[56:57], v[140:141] op_sel:[1,0,0]
	v_pk_fma_f32 v[54:55], v[74:75], v[54:55], v[138:139] op_sel:[1,0,0]
	v_cvt_pk_f16_f32 v63, v68, v69
	v_cvt_pk_f16_f32 v64, v64, v65
	v_cvt_pk_f16_f32 v65, v72, v73
	v_addc_co_u32_e32 v67, vcc, 0, v177, vcc
	v_max_f32_e32 v61, 0, v61
	v_max_f32_e32 v60, 0, v60
	v_max_f32_e32 v59, 0, v59
	v_max_f32_e32 v58, 0, v58
	v_max_f32_e32 v57, 0, v57
	v_max_f32_e32 v56, 0, v56
	v_max_f32_e32 v55, 0, v55
	v_max_f32_e32 v54, 0, v54
	v_pk_fma_f32 v[50:51], v[162:163], v[76:77], v[50:51] op_sel_hi:[1,0,1] neg_lo:[1,0,0] neg_hi:[1,0,0]
	global_store_dwordx4 v[66:67], v[62:65], off nt
	v_pk_mul_f32 v[60:61], v[60:61], v[60:61]
	v_pk_mul_f32 v[58:59], v[58:59], v[58:59]
	v_pk_mul_f32 v[62:63], v[56:57], v[56:57]
	v_pk_mul_f32 v[56:57], v[54:55], v[54:55]
	v_pk_fma_f32 v[52:53], v[164:165], v[76:77], v[52:53] op_sel_hi:[1,0,1]
	v_pk_fma_f32 v[50:51], v[76:77], v[50:51], v[158:159] op_sel:[1,0,0]
	v_pk_fma_f32 v[48:49], v[130:131], v[76:77], v[48:49] op_sel_hi:[1,0,1]
	v_pk_fma_f32 v[46:47], v[154:155], v[76:77], v[46:47] op_sel_hi:[1,0,1] neg_lo:[1,0,0] neg_hi:[1,0,0]
	v_cvt_pk_f16_f32 v54, v58, v59
	v_cvt_pk_f16_f32 v55, v60, v61
	v_cvt_pk_f16_f32 v56, v56, v57
	v_cvt_pk_f16_f32 v57, v62, v63
	s_mov_b64 s[12:13], 0x120000
	v_pk_fma_f32 v[52:53], v[76:77], v[52:53], v[160:161] op_sel:[1,0,0]
	v_pk_fma_f32 v[48:49], v[76:77], v[48:49], v[152:153] op_sel:[1,0,0]
	v_pk_fma_f32 v[46:47], v[76:77], v[46:47], v[150:151] op_sel:[1,0,0]
	v_max_f32_e32 v51, 0, v51
	v_max_f32_e32 v50, 0, v50
	v_pk_fma_f32 v[44:45], v[126:127], v[76:77], v[44:45] op_sel_hi:[1,0,1]
	v_pk_fma_f32 v[42:43], v[142:143], v[76:77], v[42:43] op_sel_hi:[1,0,1] neg_lo:[1,0,0] neg_hi:[1,0,0]
	global_store_dwordx4 v[70:71], v[54:57], off offset:256 nt
	v_max_f32_e32 v53, 0, v53
	v_max_f32_e32 v52, 0, v52
	v_lshl_add_u64 v[54:55], v[176:177], 0, s[12:13]
	v_max_f32_e32 v49, 0, v49
	v_max_f32_e32 v48, 0, v48
	v_max_f32_e32 v47, 0, v47
	v_max_f32_e32 v46, 0, v46
	v_pk_mul_f32 v[50:51], v[50:51], v[50:51]
	s_mov_b32 s12, 0x120000
	v_pk_fma_f32 v[44:45], v[76:77], v[44:45], v[148:149] op_sel:[1,0,0]
	v_pk_fma_f32 v[42:43], v[76:77], v[42:43], v[146:147] op_sel:[1,0,0]
	v_pk_fma_f32 v[40:41], v[122:123], v[76:77], v[40:41] op_sel_hi:[1,0,1]
	v_pk_fma_f32 v[38:39], v[134:135], v[76:77], v[38:39] op_sel_hi:[1,0,1] neg_lo:[1,0,0] neg_hi:[1,0,0]
	v_pk_mul_f32 v[52:53], v[52:53], v[52:53]
	v_pk_mul_f32 v[56:57], v[48:49], v[48:49]
	v_pk_mul_f32 v[48:49], v[46:47], v[46:47]
	v_cvt_pk_f16_f32 v46, v50, v51
	v_add_co_u32_e32 v50, vcc, s12, v176
	v_pk_fma_f32 v[40:41], v[76:77], v[40:41], v[140:141] op_sel:[1,0,0]
	v_pk_fma_f32 v[38:39], v[76:77], v[38:39], v[138:139] op_sel:[1,0,0]
	v_max_f32_e32 v45, 0, v45
	v_max_f32_e32 v44, 0, v44
	v_max_f32_e32 v43, 0, v43
	v_max_f32_e32 v42, 0, v42
	v_cvt_pk_f16_f32 v47, v52, v53
	v_cvt_pk_f16_f32 v48, v48, v49
	v_cvt_pk_f16_f32 v49, v56, v57
	v_addc_co_u32_e32 v51, vcc, 0, v177, vcc
	v_max_f32_e32 v41, 0, v41
	v_max_f32_e32 v40, 0, v40
	v_max_f32_e32 v39, 0, v39
	v_max_f32_e32 v38, 0, v38
	v_pk_mul_f32 v[44:45], v[44:45], v[44:45]
	v_pk_mul_f32 v[42:43], v[42:43], v[42:43]
	global_store_dwordx4 v[50:51], v[46:49], off nt
	s_mov_b64 s[12:13], 0x140000
	v_readlane_b32 s55, v255, 26
	v_pk_mul_f32 v[46:47], v[40:41], v[40:41]
	v_pk_mul_f32 v[40:41], v[38:39], v[38:39]
	v_cvt_pk_f16_f32 v38, v42, v43
	v_cvt_pk_f16_f32 v39, v44, v45
	ds_read2_b64 v[42:45], v185 offset0:160 offset1:176
	v_cvt_pk_f16_f32 v40, v40, v41
	v_cvt_pk_f16_f32 v41, v46, v47
	global_store_dwordx4 v[54:55], v[38:41], off offset:256 nt
	s_waitcnt lgkmcnt(0)
;     __device__ __forceinline__ void operator()(const f32x4 (&acc)[2][2][4][2], const Unit& u, int ui, int wr, int wc, int fr, int fq) const {
;     ...
;             for (int m = 0; m < 4; ++m) { const int row = row0 + ai * HALF + m * 16; const size_t off = (size_t)row * ldc + col0;
;                 float mu = 0.f, rs = 1.f; if (FOLD) { const f32x2_t ms = ((const PG8_LAS f32x2_t*)tb)[pslot + ai * HALF + wr * 64 + m * 16 + fr]; mu = ms.x; rs = ms.y; }
;                 float ssum = 0.f, ssq = 0.f;
; #pragma unroll
;                 for (int bj = 0; bj < 2; ++bj) { f32x4 v0 = acc[ai][bj][m][0], v1 = acc[ai][bj][m][1];
;                     if (FOLD && MODE != 2) { v0 = (v0 - mu * cv[bj][0]) * rs + bv[bj][0]; v1 = (v1 - mu * cv[bj][1]) * rs + bv[bj][1]; }
;                     if (MODE == 0) { v0 = v0 * sc; v1 = v1 * sc; }
;                     if (MODE == 1) { v0 = __builtin_elementwise_max(v0, (f32x4){0.f, 0.f, 0.f, 0.f}); v1 = __builtin_elementwise_max(v1, (f32x4){0.f, 0.f, 0.f, 0.f}); v0 = v0 * v0; v1 = v1 * v1; }
;                     if (MODE == 2) { const bf16x8 r = rr[m][bj];
;                         f32x4 h0 = (f32x4){(float)r[0], (float)r[1], (float)r[2], (float)r[3]}, h1 = (f32x4){(float)r[4], (float)r[5], (float)r[6], (float)r[7]};
;                         if (FOLD) { h0 = (h0 - mu) * rs * cv[bj][0] + bv[bj][0]; h1 = (h1 - mu) * rs * cv[bj][1] + bv[bj][1]; }
;                         v0 = v0 + alpha * h0; v1 = v1 + alpha * h1;
;                         ssum += (v0[0] + v0[1]) + (v0[2] + v0[3]) + (v1[0] + v1[1]) + (v1[2] + v1[3]);
;                         ssq += (v0[0] * v0[0] + v0[1] * v0[1]) + (v0[2] * v0[2] + v0[3] * v0[3]) + (v1[0] * v1[0] + v1[1] * v1[1]) + (v1[2] * v1[2] + v1[3] * v1[3]); }
;                     u32x4 w; w.x = pk2h(v0[0], v0[1]); w.y = pk2h(v0[2], v0[3]); w.z = pk2h(v1[0], v1[1]); w.w = pk2h(v1[2], v1[3]);
;                     if (MODE == 0 && hm) { const int cc = col0 + bj * HALF; *(u32x4*)(base + ((size_t)(row >> 11) * 16 + (cc >> 6)) * 131072 + (size_t)(row & 2047) * 64 + (cc & 63)) = w; }
;                     else *(u32x4*)(base + off + bj * HALF) = w; }
; template <class Epi, class Sched, bool ALIGN_EPI = false, bool SP2 = false>
; __device__ __forceinline__ void gemm_phase(PG8_LAS unsigned char* lds, const Gemm g, const Sched& S, const Epi& E) {
;     ...
;         if (!has_next) break;
; #pragma unroll
	v_pk_fma_f32 v[34:35], v[162:163], v[42:43], v[34:35] op_sel_hi:[1,0,1] neg_lo:[1,0,0] neg_hi:[1,0,0]
	v_pk_fma_f32 v[36:37], v[164:165], v[42:43], v[36:37] op_sel_hi:[1,0,1]
	v_pk_fma_f32 v[34:35], v[42:43], v[34:35], v[158:159] op_sel:[1,0,0]
	v_pk_fma_f32 v[32:33], v[130:131], v[42:43], v[32:33] op_sel_hi:[1,0,1]
	v_pk_fma_f32 v[30:31], v[154:155], v[42:43], v[30:31] op_sel_hi:[1,0,1] neg_lo:[1,0,0] neg_hi:[1,0,0]
	v_pk_fma_f32 v[36:37], v[42:43], v[36:37], v[160:161] op_sel:[1,0,0]
	v_pk_fma_f32 v[32:33], v[42:43], v[32:33], v[152:153] op_sel:[1,0,0]
	v_pk_fma_f32 v[30:31], v[42:43], v[30:31], v[150:151] op_sel:[1,0,0]
	v_max_f32_e32 v35, 0, v35
	v_max_f32_e32 v34, 0, v34
	v_lshl_add_u64 v[38:39], v[176:177], 0, s[12:13]
	v_max_f32_e32 v37, 0, v37
	v_max_f32_e32 v36, 0, v36
	v_max_f32_e32 v33, 0, v33
	v_max_f32_e32 v32, 0, v32
	v_max_f32_e32 v31, 0, v31
	v_max_f32_e32 v30, 0, v30
	v_pk_mul_f32 v[34:35], v[34:35], v[34:35]
	s_mov_b32 s12, 0x140000
	v_pk_fma_f32 v[28:29], v[126:127], v[42:43], v[28:29] op_sel_hi:[1,0,1]
	v_pk_fma_f32 v[26:27], v[142:143], v[42:43], v[26:27] op_sel_hi:[1,0,1] neg_lo:[1,0,0] neg_hi:[1,0,0]
	v_pk_fma_f32 v[24:25], v[122:123], v[42:43], v[24:25] op_sel_hi:[1,0,1]
	v_pk_fma_f32 v[22:23], v[134:135], v[42:43], v[22:23] op_sel_hi:[1,0,1] neg_lo:[1,0,0] neg_hi:[1,0,0]
	v_pk_mul_f32 v[36:37], v[36:37], v[36:37]
	v_pk_mul_f32 v[40:41], v[32:33], v[32:33]
	v_pk_mul_f32 v[32:33], v[30:31], v[30:31]
	v_cvt_pk_f16_f32 v30, v34, v35
	v_add_co_u32_e32 v34, vcc, s12, v176
	v_pk_fma_f32 v[28:29], v[42:43], v[28:29], v[148:149] op_sel:[1,0,0]
	v_pk_fma_f32 v[26:27], v[42:43], v[26:27], v[146:147] op_sel:[1,0,0]
	v_pk_fma_f32 v[24:25], v[42:43], v[24:25], v[140:141] op_sel:[1,0,0]
	v_pk_fma_f32 v[22:23], v[42:43], v[22:23], v[138:139] op_sel:[1,0,0]
	v_cvt_pk_f16_f32 v31, v36, v37
	v_cvt_pk_f16_f32 v32, v32, v33
	v_cvt_pk_f16_f32 v33, v40, v41
	v_addc_co_u32_e32 v35, vcc, 0, v177, vcc
	v_max_f32_e32 v29, 0, v29
	v_max_f32_e32 v28, 0, v28
	v_max_f32_e32 v27, 0, v27
	v_max_f32_e32 v26, 0, v26
	v_max_f32_e32 v25, 0, v25
	v_max_f32_e32 v24, 0, v24
	v_max_f32_e32 v23, 0, v23
	v_max_f32_e32 v22, 0, v22
	v_pk_fma_f32 v[18:19], v[162:163], v[44:45], v[18:19] op_sel_hi:[1,0,1] neg_lo:[1,0,0] neg_hi:[1,0,0]
	global_store_dwordx4 v[34:35], v[30:33], off nt
	v_pk_mul_f32 v[28:29], v[28:29], v[28:29]
	v_pk_mul_f32 v[26:27], v[26:27], v[26:27]
	v_pk_mul_f32 v[30:31], v[24:25], v[24:25]
	v_pk_mul_f32 v[24:25], v[22:23], v[22:23]
	v_pk_fma_f32 v[20:21], v[164:165], v[44:45], v[20:21] op_sel_hi:[1,0,1]
	v_pk_fma_f32 v[18:19], v[44:45], v[18:19], v[158:159] op_sel:[1,0,0]
	v_pk_fma_f32 v[12:13], v[130:131], v[44:45], v[12:13] op_sel_hi:[1,0,1]
	v_pk_fma_f32 v[10:11], v[154:155], v[44:45], v[10:11] op_sel_hi:[1,0,1] neg_lo:[1,0,0] neg_hi:[1,0,0]
	v_cvt_pk_f16_f32 v22, v26, v27
	v_cvt_pk_f16_f32 v23, v28, v29
	v_cvt_pk_f16_f32 v24, v24, v25
	v_cvt_pk_f16_f32 v25, v30, v31
	s_mov_b64 s[12:13], 0x160000
	v_pk_fma_f32 v[20:21], v[44:45], v[20:21], v[160:161] op_sel:[1,0,0]
	v_pk_fma_f32 v[12:13], v[44:45], v[12:13], v[152:153] op_sel:[1,0,0]
	v_pk_fma_f32 v[10:11], v[44:45], v[10:11], v[150:151] op_sel:[1,0,0]
	v_max_f32_e32 v19, 0, v19
	v_max_f32_e32 v18, 0, v18
	global_store_dwordx4 v[38:39], v[22:25], off offset:256 nt
	v_max_f32_e32 v21, 0, v21
	v_max_f32_e32 v20, 0, v20
	v_lshl_add_u64 v[22:23], v[176:177], 0, s[12:13]
	v_max_f32_e32 v13, 0, v13
	v_max_f32_e32 v12, 0, v12
	v_max_f32_e32 v11, 0, v11
	v_max_f32_e32 v10, 0, v10
	v_pk_mul_f32 v[18:19], v[18:19], v[18:19]
	s_mov_b32 s12, 0x160000
	v_pk_fma_f32 v[8:9], v[126:127], v[44:45], v[8:9] op_sel_hi:[1,0,1]
	v_pk_fma_f32 v[6:7], v[142:143], v[44:45], v[6:7] op_sel_hi:[1,0,1] neg_lo:[1,0,0] neg_hi:[1,0,0]
	v_pk_fma_f32 v[4:5], v[122:123], v[44:45], v[4:5] op_sel_hi:[1,0,1]
	v_pk_fma_f32 v[2:3], v[134:135], v[44:45], v[2:3] op_sel_hi:[1,0,1] neg_lo:[1,0,0] neg_hi:[1,0,0]
	v_pk_mul_f32 v[20:21], v[20:21], v[20:21]
	v_pk_mul_f32 v[24:25], v[12:13], v[12:13]
	v_pk_mul_f32 v[12:13], v[10:11], v[10:11]
	v_cvt_pk_f16_f32 v10, v18, v19
	v_add_co_u32_e32 v18, vcc, s12, v176
	v_pk_fma_f32 v[8:9], v[44:45], v[8:9], v[148:149] op_sel:[1,0,0]
	v_pk_fma_f32 v[6:7], v[44:45], v[6:7], v[146:147] op_sel:[1,0,0]
	v_pk_fma_f32 v[4:5], v[44:45], v[4:5], v[140:141] op_sel:[1,0,0]
	v_pk_fma_f32 v[2:3], v[44:45], v[2:3], v[138:139] op_sel:[1,0,0]
	v_cvt_pk_f16_f32 v11, v20, v21
	v_cvt_pk_f16_f32 v12, v12, v13
	v_cvt_pk_f16_f32 v13, v24, v25
	v_addc_co_u32_e32 v19, vcc, 0, v177, vcc
	v_max_f32_e32 v9, 0, v9
	v_max_f32_e32 v8, 0, v8
	v_max_f32_e32 v7, 0, v7
	v_max_f32_e32 v6, 0, v6
	v_max_f32_e32 v5, 0, v5
	v_max_f32_e32 v4, 0, v4
	v_max_f32_e32 v3, 0, v3
	v_max_f32_e32 v2, 0, v2
	global_store_dwordx4 v[18:19], v[10:13], off nt
	v_pk_mul_f32 v[8:9], v[8:9], v[8:9]
	v_pk_mul_f32 v[6:7], v[6:7], v[6:7]
	v_pk_mul_f32 v[10:11], v[4:5], v[4:5]
	v_pk_mul_f32 v[4:5], v[2:3], v[2:3]
	v_cvt_pk_f16_f32 v2, v6, v7
	v_cvt_pk_f16_f32 v3, v8, v9
	v_cvt_pk_f16_f32 v4, v4, v5
	v_cvt_pk_f16_f32 v5, v10, v11
	s_andn2_b64 vcc, exec, s[36:37]
	global_store_dwordx4 v[22:23], v[2:5], off offset:256 nt
	s_cbranch_vccnz .LBB0_978
	s_andn2_b64 vcc, exec, s[8:9]
	s_cbranch_vccnz .LBB0_977
	s_barrier
	s_branch .LBB0_977
